# adds: FFN-up epilogue drops canonicalising v_max x,x,x and folds v_max pairs (107 fewer VALU per wave per tile), store-data WAR padding kept
# speedup vs baseline: 1.0111x; 1.0044x over previous
; __device__ __forceinline__ unsigned cvt_pk_bf16(float lo, float hi) { unsigned r; asm volatile("v_cvt_pk_bf16_f32 %0, %1, %2" : "=v"(r) : "v"(lo), "v"(hi)); return r; }
;     __device__ __forceinline__ void operator()(const f32x4 (&acc)[2][2][4][2], const Unit& u, int wr, int wc, int fr, int fq) const {
;     ...
;             for (int m = 0; m < 4; ++m) { bf16_t* rowp = O + (size_t)(row0 + ai * HALF + m * 16) * ldc + col0;
; #pragma unroll
;                 for (int bj = 0; bj < 2; ++bj) { f32x4 v0 = acc[ai][bj][m][0], v1 = acc[ai][bj][m][1];
; #pragma unroll
;                     for (int e = 0; e < 4; ++e) { const float a = fmaxf(v0[e], 0.f), b = fmaxf(v1[e], 0.f); v0[e] = a * a; v1[e] = b * b; }
;                     u32x4 w; w.x = cvt_pk_bf16(v0[0], v0[1]); w.y = cvt_pk_bf16(v0[2], v0[3]); w.z = cvt_pk_bf16(v1[0], v1[1]); w.w = cvt_pk_bf16(v1[2], v1[3]);
;                     __builtin_nontemporal_store(w, (u32x4*)(rowp + bj * HALF)); } }
.LBB0_886:
	v_lshl_add_u32 v152, s22, 8, v146
	v_ashrrev_i32_e32 v153, 31, v152
	v_max_f32_e32 v120, 0, v120
	v_lshl_or_b32 v144, s40, 8, v148
	v_lshlrev_b64 v[154:155], 13, v[152:153]
	v_readlane_b32 s24, v251, 40
	v_mul_f32_e32 v153, v120, v120
	v_max_f32_e32 v120, 0, v125
	v_max_f32_e32 v121, 0, v121
	v_max_f32_e32 v122, 0, v122
	v_ashrrev_i32_e32 v145, 31, v144
	v_readlane_b32 s25, v251, 41
	v_mul_f32_e32 v125, v121, v121
	v_max_f32_e32 v121, v126, v126
	v_mul_f32_e32 v126, v122, v122
	v_max_f32_e32 v122, 0, v127
	v_lshl_add_u64 v[154:155], s[24:25], 0, v[154:155]
	v_lshlrev_b64 v[156:157], 1, v[144:145]
	v_max_f32_e32 v124, 0, v124
	v_mul_f32_e32 v120, v120, v120
	v_max_f32_e32 v121, 0, v121
	v_max_f32_e32 v123, 0, v123
	v_lshl_add_u64 v[144:145], v[154:155], 0, v[156:157]
	v_mul_f32_e32 v124, v124, v124
	v_mul_f32_e32 v121, v121, v121
	v_mul_f32_e32 v122, v122, v122
	v_mul_f32_e32 v123, v123, v123
	v_cvt_pk_bf16_f32 v120, v124, v120
	v_max_f32_e32 v112, 0, v112
	v_cvt_pk_bf16_f32 v121, v121, v122
	v_cvt_pk_bf16_f32 v122, v153, v125
	v_cvt_pk_bf16_f32 v123, v126, v123
	global_store_dwordx4 v[144:145], v[120:123], off nt
	v_max_f32_e32 v113, 0, v113
	v_max_f32_e32 v114, 0, v114
	v_mul_f32_e32 v120, v112, v112
	v_max_f32_e32 v112, 0, v117
	v_mul_f32_e32 v117, v113, v113
	v_max_f32_e32 v113, v118, v118
	v_mul_f32_e32 v118, v114, v114
	v_max_f32_e32 v114, 0, v119
	v_max_f32_e32 v116, 0, v116
	v_mul_f32_e32 v112, v112, v112
	v_max_f32_e32 v113, 0, v113
	v_max_f32_e32 v115, 0, v115
	v_mul_f32_e32 v116, v116, v116
	v_mul_f32_e32 v113, v113, v113
	v_mul_f32_e32 v114, v114, v114
	v_mul_f32_e32 v115, v115, v115
	v_cvt_pk_bf16_f32 v112, v116, v112
	v_cvt_pk_bf16_f32 v113, v113, v114
	v_cvt_pk_bf16_f32 v114, v120, v117
	v_cvt_pk_bf16_f32 v115, v118, v115
	global_store_dwordx4 v[144:145], v[112:115], off offset:256 nt
	s_nop 1
	v_max_f32_e32 v104, 0, v104
	v_or_b32_e32 v112, 16, v152
	v_ashrrev_i32_e32 v113, 31, v112
	v_mul_f32_e32 v114, v104, v104
	v_max_f32_e32 v104, 0, v109
	v_max_f32_e32 v105, 0, v105
	v_max_f32_e32 v106, 0, v106
	v_lshlrev_b64 v[112:113], 13, v[112:113]
	v_mul_f32_e32 v109, v105, v105
	v_max_f32_e32 v105, v110, v110
	v_mul_f32_e32 v110, v106, v106
	v_max_f32_e32 v106, 0, v111
	v_lshl_add_u64 v[112:113], s[24:25], 0, v[112:113]
	v_max_f32_e32 v108, 0, v108
	v_mul_f32_e32 v104, v104, v104
	v_max_f32_e32 v105, 0, v105
	v_max_f32_e32 v107, 0, v107
	v_lshl_add_u64 v[112:113], v[112:113], 0, v[156:157]
	v_mul_f32_e32 v108, v108, v108
	v_mul_f32_e32 v105, v105, v105
	v_mul_f32_e32 v106, v106, v106
	v_mul_f32_e32 v107, v107, v107
	v_cvt_pk_bf16_f32 v104, v108, v104
	v_max_f32_e32 v96, 0, v96
	v_cvt_pk_bf16_f32 v105, v105, v106
	v_cvt_pk_bf16_f32 v106, v114, v109
	v_cvt_pk_bf16_f32 v107, v110, v107
	global_store_dwordx4 v[112:113], v[104:107], off nt
	v_max_f32_e32 v97, 0, v97
	v_max_f32_e32 v98, 0, v98
	v_mul_f32_e32 v104, v96, v96
	v_max_f32_e32 v96, 0, v101
	v_mul_f32_e32 v101, v97, v97
	v_max_f32_e32 v97, v102, v102
	v_mul_f32_e32 v102, v98, v98
	v_max_f32_e32 v98, 0, v103
	v_max_f32_e32 v100, 0, v100
	v_mul_f32_e32 v96, v96, v96
	v_max_f32_e32 v97, 0, v97
	v_max_f32_e32 v99, 0, v99
	v_mul_f32_e32 v100, v100, v100
	v_mul_f32_e32 v97, v97, v97
	v_mul_f32_e32 v98, v98, v98
	v_mul_f32_e32 v99, v99, v99
	v_cvt_pk_bf16_f32 v96, v100, v96
	v_cvt_pk_bf16_f32 v97, v97, v98
	v_cvt_pk_bf16_f32 v98, v104, v101
	v_cvt_pk_bf16_f32 v99, v102, v99
	global_store_dwordx4 v[112:113], v[96:99], off offset:256 nt
	s_nop 1
	v_max_f32_e32 v88, 0, v88
	v_or_b32_e32 v96, 32, v152
	v_ashrrev_i32_e32 v97, 31, v96
	v_mul_f32_e32 v98, v88, v88
	v_max_f32_e32 v88, 0, v93
	v_max_f32_e32 v89, 0, v89
	v_max_f32_e32 v90, 0, v90
	v_lshlrev_b64 v[96:97], 13, v[96:97]
	v_mul_f32_e32 v93, v89, v89
	v_max_f32_e32 v89, v94, v94
	v_mul_f32_e32 v94, v90, v90
	v_max_f32_e32 v90, 0, v95
	v_lshl_add_u64 v[96:97], s[24:25], 0, v[96:97]
	v_max_f32_e32 v92, 0, v92
	v_mul_f32_e32 v88, v88, v88
	v_max_f32_e32 v89, 0, v89
	v_max_f32_e32 v91, 0, v91
	v_lshl_add_u64 v[96:97], v[96:97], 0, v[156:157]
	v_mul_f32_e32 v92, v92, v92
	v_mul_f32_e32 v89, v89, v89
	v_mul_f32_e32 v90, v90, v90
	v_mul_f32_e32 v91, v91, v91
	v_cvt_pk_bf16_f32 v88, v92, v88
	v_max_f32_e32 v80, 0, v80
	v_cvt_pk_bf16_f32 v89, v89, v90
	v_cvt_pk_bf16_f32 v90, v98, v93
	v_cvt_pk_bf16_f32 v91, v94, v91
	global_store_dwordx4 v[96:97], v[88:91], off nt
	v_max_f32_e32 v81, 0, v81
	v_max_f32_e32 v82, 0, v82
	v_mul_f32_e32 v88, v80, v80
	v_max_f32_e32 v80, 0, v85
	v_mul_f32_e32 v85, v81, v81
	v_max_f32_e32 v81, v86, v86
	v_mul_f32_e32 v86, v82, v82
	v_max_f32_e32 v82, 0, v87
	v_max_f32_e32 v84, 0, v84
	v_mul_f32_e32 v80, v80, v80
	v_max_f32_e32 v81, 0, v81
	v_max_f32_e32 v83, 0, v83
	v_mul_f32_e32 v84, v84, v84
	v_mul_f32_e32 v81, v81, v81
	v_mul_f32_e32 v82, v82, v82
	v_mul_f32_e32 v83, v83, v83
	v_cvt_pk_bf16_f32 v80, v84, v80
	v_cvt_pk_bf16_f32 v81, v81, v82
	v_cvt_pk_bf16_f32 v82, v88, v85
	v_cvt_pk_bf16_f32 v83, v86, v83
	global_store_dwordx4 v[96:97], v[80:83], off offset:256 nt
	s_nop 1
	v_max_f32_e32 v72, 0, v72
	v_or_b32_e32 v80, 48, v152
	v_ashrrev_i32_e32 v81, 31, v80
	v_mul_f32_e32 v82, v72, v72
	v_max_f32_e32 v72, 0, v77
	v_max_f32_e32 v73, 0, v73
	v_max_f32_e32 v74, 0, v74
	v_lshlrev_b64 v[80:81], 13, v[80:81]
	v_mul_f32_e32 v77, v73, v73
	v_max_f32_e32 v73, v78, v78
	v_mul_f32_e32 v78, v74, v74
	v_max_f32_e32 v74, 0, v79
	v_lshl_add_u64 v[80:81], s[24:25], 0, v[80:81]
	v_max_f32_e32 v76, 0, v76
	v_mul_f32_e32 v72, v72, v72
	v_max_f32_e32 v73, 0, v73
	v_max_f32_e32 v75, 0, v75
	v_lshl_add_u64 v[80:81], v[80:81], 0, v[156:157]
	v_mul_f32_e32 v76, v76, v76
	v_mul_f32_e32 v73, v73, v73
	v_mul_f32_e32 v74, v74, v74
; __device__ __forceinline__ unsigned cvt_pk_bf16(float lo, float hi) { unsigned r; asm volatile("v_cvt_pk_bf16_f32 %0, %1, %2" : "=v"(r) : "v"(lo), "v"(hi)); return r; }
;     __device__ __forceinline__ void operator()(const f32x4 (&acc)[2][2][4][2], const Unit& u, int wr, int wc, int fr, int fq) const {
;     ...
;             for (int m = 0; m < 4; ++m) { bf16_t* rowp = O + (size_t)(row0 + ai * HALF + m * 16) * ldc + col0;
; #pragma unroll
;                 for (int bj = 0; bj < 2; ++bj) { f32x4 v0 = acc[ai][bj][m][0], v1 = acc[ai][bj][m][1];
; #pragma unroll
;                     for (int e = 0; e < 4; ++e) { const float a = fmaxf(v0[e], 0.f), b = fmaxf(v1[e], 0.f); v0[e] = a * a; v1[e] = b * b; }
;                     u32x4 w; w.x = cvt_pk_bf16(v0[0], v0[1]); w.y = cvt_pk_bf16(v0[2], v0[3]); w.z = cvt_pk_bf16(v1[0], v1[1]); w.w = cvt_pk_bf16(v1[2], v1[3]);
;                     __builtin_nontemporal_store(w, (u32x4*)(rowp + bj * HALF)); } }
	v_mul_f32_e32 v75, v75, v75
	v_cvt_pk_bf16_f32 v72, v76, v72
	v_max_f32_e32 v64, 0, v64
	v_max_f32_e32 v65, 0, v65
	v_max_f32_e32 v66, 0, v66
	v_cvt_pk_bf16_f32 v73, v73, v74
	v_cvt_pk_bf16_f32 v74, v82, v77
	v_cvt_pk_bf16_f32 v75, v78, v75
	global_store_dwordx4 v[80:81], v[72:75], off nt
	s_nop 1
	v_mul_f32_e32 v72, v64, v64
	v_max_f32_e32 v64, v69, v69
	v_mul_f32_e32 v69, v65, v65
	v_max_f32_e32 v65, v70, v70
	v_mul_f32_e32 v70, v66, v66
	v_max_f32_e32 v66, 0, v71
	v_max_f32_e32 v64, 0, v64
	v_max_f32_e32 v65, 0, v65
	v_max_f32_e32 v68, 0, v68
	v_mul_f32_e32 v64, v64, v64
	v_mul_f32_e32 v65, v65, v65
	v_max_f32_e32 v67, 0, v67
	v_mul_f32_e32 v66, v66, v66
	v_mul_f32_e32 v68, v68, v68
	v_mul_f32_e32 v67, v67, v67
	v_cvt_pk_bf16_f32 v64, v68, v64
	v_cvt_pk_bf16_f32 v65, v65, v66
	v_cvt_pk_bf16_f32 v66, v72, v69
	v_max_f32_e32 v56, 0, v56
	v_cvt_pk_bf16_f32 v67, v70, v67
	global_store_dwordx4 v[80:81], v[64:67], off offset:256 nt
	s_nop 1
	v_max_f32_e32 v57, 0, v57
	v_mul_f32_e32 v66, v56, v56
	v_max_f32_e32 v56, 0, v61
	v_max_f32_e32 v58, 0, v58
	v_max_f32_e32 v60, 0, v60
	v_mul_f32_e32 v61, v57, v57
	v_max_f32_e32 v57, v62, v62
	v_mul_f32_e32 v62, v58, v58
	v_max_f32_e32 v58, 0, v63
	v_mul_f32_e32 v60, v60, v60
	v_mul_f32_e32 v56, v56, v56
	v_max_f32_e32 v57, 0, v57
	s_mov_b32 s15, 0x100000
	v_mul_f32_e32 v57, v57, v57
	v_max_f32_e32 v59, 0, v59
	v_mul_f32_e32 v58, v58, v58
	v_cvt_pk_bf16_f32 v56, v60, v56
	v_add_co_u32_e32 v60, vcc, s15, v144
	v_mul_f32_e32 v59, v59, v59
	v_cvt_pk_bf16_f32 v57, v57, v58
	v_cvt_pk_bf16_f32 v58, v66, v61
	v_addc_co_u32_e32 v61, vcc, 0, v145, vcc
	v_max_f32_e32 v48, 0, v48
	v_max_f32_e32 v49, 0, v49
	v_max_f32_e32 v50, 0, v50
	v_cvt_pk_bf16_f32 v59, v62, v59
	global_store_dwordx4 v[60:61], v[56:59], off nt
	s_nop 1
	v_mul_f32_e32 v56, v48, v48
	v_max_f32_e32 v48, v53, v53
	v_mul_f32_e32 v53, v49, v49
	v_max_f32_e32 v49, v54, v54
	v_mul_f32_e32 v54, v50, v50
	v_max_f32_e32 v50, 0, v55
	v_max_f32_e32 v48, 0, v48
	v_max_f32_e32 v49, 0, v49
	s_mov_b64 s[24:25], 0x100000
	v_max_f32_e32 v52, 0, v52
	v_mul_f32_e32 v48, v48, v48
	v_mul_f32_e32 v49, v49, v49
	v_max_f32_e32 v51, 0, v51
	v_mul_f32_e32 v50, v50, v50
	v_lshl_add_u64 v[64:65], v[144:145], 0, s[24:25]
	v_mul_f32_e32 v52, v52, v52
	v_mul_f32_e32 v51, v51, v51
	v_cvt_pk_bf16_f32 v48, v52, v48
	v_cvt_pk_bf16_f32 v49, v49, v50
	v_cvt_pk_bf16_f32 v50, v56, v53
	v_max_f32_e32 v40, 0, v40
	v_cvt_pk_bf16_f32 v51, v54, v51
	global_store_dwordx4 v[64:65], v[48:51], off offset:256 nt
	s_nop 1
	v_max_f32_e32 v41, 0, v41
	v_mul_f32_e32 v50, v40, v40
	v_max_f32_e32 v40, 0, v45
	v_max_f32_e32 v42, 0, v42
	v_max_f32_e32 v44, 0, v44
	v_mul_f32_e32 v45, v41, v41
	v_max_f32_e32 v41, v46, v46
	v_mul_f32_e32 v46, v42, v42
	v_max_f32_e32 v42, 0, v47
	v_mul_f32_e32 v44, v44, v44
	v_mul_f32_e32 v40, v40, v40
	v_max_f32_e32 v41, 0, v41
	s_mov_b32 s15, 0x120000
	v_mul_f32_e32 v41, v41, v41
	v_max_f32_e32 v43, 0, v43
	v_mul_f32_e32 v42, v42, v42
	v_cvt_pk_bf16_f32 v40, v44, v40
	v_add_co_u32_e32 v44, vcc, s15, v144
	v_mul_f32_e32 v43, v43, v43
	v_cvt_pk_bf16_f32 v41, v41, v42
	v_cvt_pk_bf16_f32 v42, v50, v45
	v_addc_co_u32_e32 v45, vcc, 0, v145, vcc
	v_max_f32_e32 v32, 0, v32
	v_max_f32_e32 v33, 0, v33
	v_max_f32_e32 v34, 0, v34
	v_cvt_pk_bf16_f32 v43, v46, v43
	global_store_dwordx4 v[44:45], v[40:43], off nt
	s_nop 1
	v_mul_f32_e32 v40, v32, v32
	v_max_f32_e32 v32, v37, v37
	v_mul_f32_e32 v37, v33, v33
	v_max_f32_e32 v33, v38, v38
	v_mul_f32_e32 v38, v34, v34
	v_max_f32_e32 v34, 0, v39
	v_max_f32_e32 v32, 0, v32
	v_max_f32_e32 v33, 0, v33
	s_mov_b64 s[24:25], 0x120000
	v_max_f32_e32 v36, 0, v36
; __device__ __forceinline__ unsigned cvt_pk_bf16(float lo, float hi) { unsigned r; asm volatile("v_cvt_pk_bf16_f32 %0, %1, %2" : "=v"(r) : "v"(lo), "v"(hi)); return r; }
;     __device__ __forceinline__ void operator()(const f32x4 (&acc)[2][2][4][2], const Unit& u, int wr, int wc, int fr, int fq) const {
;     ...
;             for (int m = 0; m < 4; ++m) { bf16_t* rowp = O + (size_t)(row0 + ai * HALF + m * 16) * ldc + col0;
; #pragma unroll
;                 for (int bj = 0; bj < 2; ++bj) { f32x4 v0 = acc[ai][bj][m][0], v1 = acc[ai][bj][m][1];
; #pragma unroll
;                     for (int e = 0; e < 4; ++e) { const float a = fmaxf(v0[e], 0.f), b = fmaxf(v1[e], 0.f); v0[e] = a * a; v1[e] = b * b; }
;                     u32x4 w; w.x = cvt_pk_bf16(v0[0], v0[1]); w.y = cvt_pk_bf16(v0[2], v0[3]); w.z = cvt_pk_bf16(v1[0], v1[1]); w.w = cvt_pk_bf16(v1[2], v1[3]);
;                     __builtin_nontemporal_store(w, (u32x4*)(rowp + bj * HALF)); } }
	v_mul_f32_e32 v32, v32, v32
	v_mul_f32_e32 v33, v33, v33
	v_max_f32_e32 v35, 0, v35
	v_mul_f32_e32 v34, v34, v34
	v_lshl_add_u64 v[48:49], v[144:145], 0, s[24:25]
	v_mul_f32_e32 v36, v36, v36
	v_mul_f32_e32 v35, v35, v35
	v_cvt_pk_bf16_f32 v32, v36, v32
	v_cvt_pk_bf16_f32 v33, v33, v34
	v_cvt_pk_bf16_f32 v34, v40, v37
	v_max_f32_e32 v24, 0, v24
	v_cvt_pk_bf16_f32 v35, v38, v35
	global_store_dwordx4 v[48:49], v[32:35], off offset:256 nt
	s_nop 1
	v_max_f32_e32 v25, 0, v25
	v_mul_f32_e32 v34, v24, v24
	v_max_f32_e32 v24, 0, v29
	v_max_f32_e32 v26, 0, v26
	v_max_f32_e32 v28, 0, v28
	v_mul_f32_e32 v29, v25, v25
	v_max_f32_e32 v25, v30, v30
	v_mul_f32_e32 v30, v26, v26
	v_max_f32_e32 v26, 0, v31
	v_mul_f32_e32 v28, v28, v28
	v_mul_f32_e32 v24, v24, v24
	v_max_f32_e32 v25, 0, v25
	s_mov_b32 s15, 0x140000
	v_mul_f32_e32 v25, v25, v25
	v_max_f32_e32 v27, 0, v27
	v_mul_f32_e32 v26, v26, v26
	v_cvt_pk_bf16_f32 v24, v28, v24
	v_add_co_u32_e32 v28, vcc, s15, v144
	v_mul_f32_e32 v27, v27, v27
	v_cvt_pk_bf16_f32 v25, v25, v26
	v_cvt_pk_bf16_f32 v26, v34, v29
	v_addc_co_u32_e32 v29, vcc, 0, v145, vcc
	v_max_f32_e32 v16, 0, v16
	v_max_f32_e32 v17, 0, v17
	v_max_f32_e32 v18, 0, v18
	v_cvt_pk_bf16_f32 v27, v30, v27
	global_store_dwordx4 v[28:29], v[24:27], off nt
	s_nop 1
	v_mul_f32_e32 v24, v16, v16
	v_max_f32_e32 v16, v21, v21
	v_mul_f32_e32 v21, v17, v17
	v_max_f32_e32 v17, v22, v22
	v_mul_f32_e32 v22, v18, v18
	v_max_f32_e32 v18, 0, v23
	v_max_f32_e32 v16, 0, v16
	v_max_f32_e32 v17, 0, v17
	s_mov_b64 s[24:25], 0x140000
	v_max_f32_e32 v20, 0, v20
	v_mul_f32_e32 v16, v16, v16
	v_mul_f32_e32 v17, v17, v17
	v_max_f32_e32 v19, 0, v19
	v_mul_f32_e32 v18, v18, v18
	v_lshl_add_u64 v[32:33], v[144:145], 0, s[24:25]
	v_mul_f32_e32 v20, v20, v20
	v_mul_f32_e32 v19, v19, v19
	v_cvt_pk_bf16_f32 v16, v20, v16
	v_cvt_pk_bf16_f32 v17, v17, v18
	v_cvt_pk_bf16_f32 v18, v24, v21
	v_max_f32_e32 v8, 0, v8
	v_cvt_pk_bf16_f32 v19, v22, v19
	global_store_dwordx4 v[32:33], v[16:19], off offset:256 nt
	s_nop 1
	v_max_f32_e32 v9, 0, v9
	v_mul_f32_e32 v18, v8, v8
	v_max_f32_e32 v8, 0, v13
	v_max_f32_e32 v10, 0, v10
	v_max_f32_e32 v12, 0, v12
	v_mul_f32_e32 v13, v9, v9
	v_max_f32_e32 v9, v14, v14
	v_mul_f32_e32 v14, v10, v10
	v_max_f32_e32 v10, 0, v15
	v_mul_f32_e32 v12, v12, v12
	v_mul_f32_e32 v8, v8, v8
	v_max_f32_e32 v9, 0, v9
	s_mov_b32 s15, 0x160000
	v_mul_f32_e32 v9, v9, v9
	v_max_f32_e32 v11, 0, v11
	v_mul_f32_e32 v10, v10, v10
	v_cvt_pk_bf16_f32 v8, v12, v8
	v_add_co_u32_e32 v12, vcc, s15, v144
	v_mul_f32_e32 v11, v11, v11
	v_cvt_pk_bf16_f32 v9, v9, v10
	v_cvt_pk_bf16_f32 v10, v18, v13
	v_addc_co_u32_e32 v13, vcc, 0, v145, vcc
	v_max_f32_e32 v0, 0, v0
	v_max_f32_e32 v1, 0, v1
	v_max_f32_e32 v2, 0, v2
	v_cvt_pk_bf16_f32 v11, v14, v11
	global_store_dwordx4 v[12:13], v[8:11], off nt
	s_nop 1
	s_mov_b64 s[24:25], 0x160000
	v_mul_f32_e32 v8, v0, v0
	v_max_f32_e32 v0, v5, v5
	v_mul_f32_e32 v5, v1, v1
	v_max_f32_e32 v1, v6, v6
	v_mul_f32_e32 v6, v2, v2
	v_max_f32_e32 v2, 0, v7
	v_max_f32_e32 v0, 0, v0
	v_max_f32_e32 v1, 0, v1
	v_max_f32_e32 v3, 0, v3
	v_lshl_add_u64 v[16:17], v[144:145], 0, s[24:25]
	v_max_f32_e32 v4, 0, v4
	v_mul_f32_e32 v0, v0, v0
	v_mul_f32_e32 v1, v1, v1
	v_mul_f32_e32 v2, v2, v2
	v_mul_f32_e32 v3, v3, v3
	s_andn2_b64 vcc, exec, s[0:1]
	s_mov_b64 s[0:1], -1
	v_mul_f32_e32 v4, v4, v4
	v_cvt_pk_bf16_f32 v0, v4, v0
	v_cvt_pk_bf16_f32 v1, v1, v2
	v_cvt_pk_bf16_f32 v2, v8, v5
	v_cvt_pk_bf16_f32 v3, v6, v3
	global_store_dwordx4 v[16:17], v[0:3], off offset:256 nt
	s_cbranch_vccnz .LBB0_875
	s_andn2_b64 vcc, exec, s[4:5]
	s_cbranch_vccnz .LBB0_874
	s_barrier
	s_branch .LBB0_874
